# on top of PV-MFMA hoist: dedupe redundant bias/rope LDS-DMA pieces in the steady attention loops and drop dead m0 save/restore around each DMA
# speedup vs baseline: 1.0124x; 1.0124x over previous
.LBB0_674:
	s_mul_i32 s78, s72, 0x3000
	v_lshl_add_u32 v2, s72, 8, v175
	v_add_u32_e32 v0, s78, v169
	ds_read_b128 v[96:99], v2
	ds_read_b128 v[100:103], v2 offset:32
	ds_read_b128 v[10:13], v2 offset:128
	ds_read_b128 v[112:115], v2 offset:160
	ds_read_b128 v[104:107], v2 offset:64
	ds_read_b128 v[108:111], v2 offset:96
	ds_read_b128 v[116:119], v2 offset:192
	ds_read_b128 v[120:123], v2 offset:224
	ds_read_b128 v[6:9], v0
	ds_read_b128 v[2:5], v0 offset:4096
	s_add_i32 s86, s83, -1
	s_bitcmp1_b32 s86, 0
	s_cselect_b64 s[84:85], -1, 0
	s_and_b64 vcc, exec, s[84:85]
	s_cbranch_vccnz .LBB0_676
	s_add_i32 s79, s83, 1
	s_min_i32 s72, s79, s75
	s_cmp_gt_u32 s75, s79
	s_cselect_b64 vcc, -1, 0
	s_lshl_b32 s96, s72, 6
	s_mul_i32 s72, s96, s74
	s_mov_b32 s73, s97
	s_lshl_b64 s[88:89], s[72:73], 1
	s_add_u32 s72, s80, s88
	s_addc_u32 s73, s81, s89
	s_and_b32 s79, s79, 2
	s_mul_i32 s90, s79, 0x3000
	v_cndmask_b32_e32 v0, v164, v163, vcc
	s_add_i32 s90, s90, s82
	s_mov_b32 m0, s90
	s_nop 0
	global_load_lds_dwordx4 v0, s[72:73]
	s_lshl_b64 s[72:73], s[96:97], 5
	s_add_u32 s72, s2, s72
	s_addc_u32 s73, s3, s73
	s_lshl_b32 s90, s79, 8
	s_add_i32 s90, s90, s93
	s_add_i32 s93, s83, 2
	v_cndmask_b32_e32 v0, v167, v166, vcc
	v_readfirstlane_b32 s91, v184
	s_cmp_lg_u32 s91, 0
	s_cbranch_scc1 .Lfox_skip_aux1
	s_mov_b32 m0, s90
	s_nop 0
	global_load_lds_dword v0, s[72:73]
.Lfox_skip_aux1:
	s_min_i32 s90, s93, s75
	s_cmp_gt_u32 s75, s93
	s_cselect_b64 s[72:73], -1, 0
	s_lshl_b32 s96, s90, 6
	s_mul_i32 s90, s96, s74
	s_mov_b32 s91, s97
	s_lshl_b64 s[90:91], s[90:91], 1
	s_add_u32 s90, s80, s90
	s_addc_u32 s91, s81, s91
	s_and_b32 s93, s93, 3
	s_mul_i32 s6, s93, 0x3000
	v_cndmask_b32_e64 v0, v164, v163, s[72:73]
	s_add_i32 s6, s6, s82
	s_mov_b32 m0, s6
	s_nop 0
	global_load_lds_dwordx4 v0, s[90:91]
	s_lshl_b64 s[90:91], s[96:97], 5
	s_add_u32 s90, s2, s90
	s_addc_u32 s91, s3, s91
	s_lshl_b32 s6, s93, 8
	v_readlane_b32 s93, v227, 47
	s_add_i32 s6, s6, s93
	v_cndmask_b32_e64 v0, v167, v166, s[72:73]
	v_readfirstlane_b32 s7, v184
	s_cmp_lg_u32 s7, 64
	s_cbranch_scc1 .Lfox_skip_aux2
	s_mov_b32 m0, s6
	s_nop 0
	global_load_lds_dword v0, s[90:91]
.Lfox_skip_aux2:
	s_min_i32 s6, s83, s75
	s_cmp_gt_u32 s75, s83
	s_mul_i32 s96, s94, s6
	s_cselect_b64 s[72:73], -1, 0
	s_lshl_b64 s[90:91], s[96:97], 1
	s_add_u32 s90, s0, s90
	s_addc_u32 s91, s1, s91
	s_and_b32 s6, s87, 0x6000
	s_add_i32 s6, s6, s92
	v_cndmask_b32_e64 v0, v162, v165, s[72:73]
	s_add_u32 s72, s0, s88
	s_mov_b32 m0, s6
	s_nop 0
	global_load_lds_dwordx4 v0, s[90:91]
	s_addc_u32 s73, s1, s89
	s_lshl_b32 s6, s79, 13
	v_cndmask_b32_e32 v0, v162, v165, vcc
	s_add_i32 s6, s6, s92
	s_mov_b32 m0, s6
	s_nop 0
	global_load_lds_dwordx4 v0, s[72:73]
	s_mov_b32 s90, 0x42200000

.LBB0_746:
	s_mul_i32 s78, s72, 0x3000
	v_add_u32_e32 v0, s78, v203
	ds_read_b128 v[6:9], v0
	ds_read_b128 v[2:5], v0 offset:4096
	s_add_i32 s85, s93, -1
	s_bitcmp1_b32 s85, 0
	s_cselect_b64 s[86:87], -1, 0
	s_and_b64 vcc, exec, s[86:87]
	s_cbranch_vccnz .LBB0_748
	s_add_i32 s79, s93, 1
	s_min_i32 s72, s79, s75
	s_cmp_gt_u32 s75, s79
	s_cselect_b64 vcc, -1, 0
	s_lshl_b32 s96, s72, 6
	s_mul_i32 s72, s96, s74
	s_mov_b32 s73, s97
	s_lshl_b64 s[94:95], s[72:73], 1
	s_add_u32 s72, s80, s94
	s_addc_u32 s73, s81, s95
	s_and_b32 s79, s79, 2
	s_mul_i32 s88, s79, 0x3000
	v_cndmask_b32_e32 v0, v195, v194, vcc
	s_add_i32 s89, s88, s82
	s_mov_b32 m0, s89
	s_nop 0
	global_load_lds_dwordx4 v0, s[72:73]
	s_lshl_b64 s[72:73], s[96:97], 6
	v_readlane_b32 s40, v226, 28
	v_readlane_b32 s41, v226, 29
	s_add_u32 s72, s40, s72
	s_addc_u32 s73, s41, s73
	s_add_i32 s88, s88, s2
	s_add_i32 s90, s93, 2
	v_cndmask_b32_e32 v0, v198, v197, vcc
	v_readfirstlane_b32 s89, v184
	s_cmp_ge_u32 s89, 0x100
	s_cbranch_scc1 .Lmla_skip_aux1
	s_mov_b32 m0, s88
	s_nop 0
	global_load_lds_dwordx4 v0, s[72:73]
.Lmla_skip_aux1:
	s_min_i32 s88, s90, s75
	s_cmp_gt_u32 s75, s90
	s_cselect_b64 s[72:73], -1, 0
	s_lshl_b32 s96, s88, 6
	s_mul_i32 s88, s96, s74
	s_mov_b32 s89, s97
	s_lshl_b64 s[88:89], s[88:89], 1
	s_add_u32 s88, s80, s88
	s_addc_u32 s89, s81, s89
	s_and_b32 s90, s90, 3
	s_mulk_i32 s90, 0x3000
	v_cndmask_b32_e64 v0, v195, v194, s[72:73]
	s_add_i32 s91, s90, s82
	s_mov_b32 m0, s91
	s_nop 0
	global_load_lds_dwordx4 v0, s[88:89]
	s_lshl_b64 s[88:89], s[96:97], 6
	s_add_u32 s88, s40, s88
	s_addc_u32 s89, s41, s89
	v_cndmask_b32_e64 v0, v198, v197, s[72:73]
	s_add_i32 s72, s90, s2
	v_readfirstlane_b32 s73, v184
	s_cmp_ge_u32 s73, 0x100
	s_cbranch_scc1 .Lmla_skip_aux2
	s_mov_b32 m0, s72
	s_nop 0
	global_load_lds_dwordx4 v0, s[88:89]
.Lmla_skip_aux2:
	s_min_i32 s88, s93, s75
	s_cmp_gt_u32 s75, s93
	s_mul_i32 s96, s83, s88
	s_cselect_b64 s[72:73], -1, 0
	s_lshl_b64 s[88:89], s[96:97], 1
	s_add_u32 s88, s0, s88
	s_addc_u32 s89, s1, s89
	v_cndmask_b32_e64 v0, v193, v196, s[72:73]
	s_and_b32 s72, s84, 0x6000
	s_add_i32 s72, s72, s3
	s_mov_b32 m0, s72
	s_nop 0
	global_load_lds_dwordx4 v0, s[88:89]
	s_add_u32 s72, s0, s94
	s_addc_u32 s73, s1, s95
	s_lshl_b32 s79, s79, 13
	v_cndmask_b32_e32 v0, v193, v196, vcc
	s_add_i32 s79, s79, s3
	s_mov_b32 m0, s79
	s_nop 0
	global_load_lds_dwordx4 v0, s[72:73]
	s_mov_b32 s90, 0x42200000
